# grid size as constant in the per-tile scheduling code (no scalar load per tile), on top of shared split-K tail reduction and GU epilogue rewrite
# baseline (speedup 1.0000x reference)
;     __host__ __device__ bool next(int i, Unit& u) const {
;         const long L = (long)i * G + c; if (L >= nwg) return false;
;         int wgid = (int)L; { const int q = nwg / NXCD, r = nwg % NXCD, xcd = wgid % NXCD, off = wgid / NXCD; wgid = (xcd < r ? xcd * (q + 1) : r * (q + 1) + (xcd - r) * q) + off; }
;         const int nig = WGM * nN, gid = wgid / nig, fm = gid * WGM, gsz = (nM - fm) < WGM ? (nM - fm) : WGM;
;         u.pm = fm + ((wgid % nig) % gsz); u.pn = (wgid % nig) / gsz; u.kt0 = 0; u.nt = ntf; return true;
.LBB0_489:
	s_movk_i32 s8, 0x100
	s_mov_b32 s9, 1
	s_add_i32 s65, s65, 1
	v_readlane_b32 s3, v250, 6
	s_mul_i32 s3, s65, s3
	v_mov_b64_e32 v[0:1], s[76:77]
	s_waitcnt lgkmcnt(0)
	s_mov_b32 s40, s8
	s_mul_hi_u32 s8, s65, s8
	s_add_i32 s8, s8, s3
	s_mul_i32 s3, s65, s40
	s_add_u32 s40, s3, s2
	v_readlane_b32 s3, v250, 5
	s_addc_u32 s41, s8, s3
	v_cmp_ge_i64_e32 vcc, s[40:41], v[0:1]
	v_cmp_lt_i64_e64 s[8:9], s[40:41], v[0:1]
	s_cbranch_vccnz .LBB0_495
	s_ashr_i32 s3, s40, 31
	s_lshr_b32 s3, s3, 29
	s_add_i32 s3, s40, s3
	s_and_b32 s11, s3, -8
	s_sub_i32 s11, s40, s11
	s_cmp_ge_i32 s11, s71
	s_mov_b64 s[36:37], -1
	s_cbranch_scc0 .LBB0_492
	s_sub_i32 s36, s11, s71
	s_mul_i32 s36, s36, s70
	s_mul_i32 s37, s74, s71
	s_add_i32 s38, s36, s37
	s_mov_b64 s[36:37], 0
